# HGRN2 chunk-setup gathers: running 64-bit pointers instead of recomputing each row address
# speedup vs baseline: 1.0036x; 1.0036x over previous
.LBB0_386:
	s_lshl_b32 s35, s50, 6
	s_and_b32 s50, s35, 0x780
	s_or_b32 s34, s34, s50
	v_mov_b32_e32 v10, s64
	s_lshr_b32 s34, s34, 8
	s_and_b32 s91, s35, 0x80
	v_mad_i32_i24 v10, s65, v73, v10
	s_mul_i32 s50, s34, 0x4200
	v_or_b32_e32 v8, s91, v61
	v_ashrrev_i32_e32 v11, 31, v10
	v_lshlrev_b32_e32 v30, 1, v8
	v_lshl_add_u64 v[12:13], v[10:11], 0, s[50:51]
	v_lshl_add_u64 v[8:9], s[46:47], 0, v[30:31]
	v_lshlrev_b64 v[12:13], 9, v[12:13]
	v_lshl_add_u64 v[12:13], v[8:9], 0, v[12:13]
	global_load_ushort v62, v[12:13], off
	v_mov_b64_e32 v[154:155], v[12:13]
	s_mov_b32 s94, s65
	s_ashr_i32 s95, s65, 31
	s_lshl_b64 s[94:95], s[94:95], 9
	s_cmp_gt_i32 s62, 3
	s_cselect_b64 s[60:61], -1, 0
	s_bfe_u32 s92, s35, 0x30008
	s_mulk_i32 s92, 0x4200
	s_add_i32 s62, s92, 0x84000
	s_mov_b32 s63, s51
	s_sub_u32 s96, s62, s50
	s_subb_u32 s97, s63, s51
	s_lshl_b64 s[96:97], s[96:97], 9
	s_and_b64 vcc, exec, s[60:61]
	v_mov_b32_e32 v100, v17
	s_cbranch_vccz .LBB0_388
	v_lshl_add_u64 v[12:13], v[10:11], 0, s[62:63]
	v_lshlrev_b64 v[12:13], 9, v[12:13]
	v_lshl_add_u64 v[12:13], v[8:9], 0, v[12:13]
	global_load_ushort v100, v[12:13], off
.LBB0_388:
	v_lshl_add_u64 v[154:155], v[154:155], 0, s[94:95]
	global_load_ushort v63, v[154:155], off
	v_cndmask_b32_e64 v12, 0, 1, s[60:61]
	v_cmp_ne_u32_e64 s[34:35], 1, v12
	s_andn2_b64 vcc, exec, s[60:61]
	v_mov_b32_e32 v101, v53
	s_cbranch_vccnz .LBB0_390
	v_lshl_add_u64 v[156:157], v[154:155], 0, s[96:97]
	global_load_ushort v101, v[156:157], off
.LBB0_390:
	v_lshl_add_u64 v[154:155], v[154:155], 0, s[94:95]
	global_load_ushort v64, v[154:155], off
	s_and_b64 vcc, exec, s[34:35]
	v_mov_b32_e32 v102, v18
	s_cbranch_vccnz .LBB0_392
	v_lshl_add_u64 v[156:157], v[154:155], 0, s[96:97]
	global_load_ushort v102, v[156:157], off
.LBB0_392:
	v_lshl_add_u64 v[154:155], v[154:155], 0, s[94:95]
	global_load_ushort v65, v[154:155], off
	s_and_b64 vcc, exec, s[34:35]
	v_mov_b32_e32 v103, v51
	s_cbranch_vccnz .LBB0_394
	v_lshl_add_u64 v[156:157], v[154:155], 0, s[96:97]
	global_load_ushort v103, v[156:157], off
.LBB0_394:
	v_lshl_add_u64 v[154:155], v[154:155], 0, s[94:95]
	global_load_ushort v66, v[154:155], off
	s_and_b64 vcc, exec, s[34:35]
	v_mov_b32_e32 v104, v19
	s_cbranch_vccnz .LBB0_396
	v_lshl_add_u64 v[156:157], v[154:155], 0, s[96:97]
	global_load_ushort v104, v[156:157], off
.LBB0_396:
	v_lshl_add_u64 v[154:155], v[154:155], 0, s[94:95]
	global_load_ushort v67, v[154:155], off
	s_and_b64 vcc, exec, s[34:35]
	v_mov_b32_e32 v105, v49
	s_cbranch_vccnz .LBB0_398
	v_lshl_add_u64 v[156:157], v[154:155], 0, s[96:97]
	global_load_ushort v105, v[156:157], off
.LBB0_398:
	v_lshl_add_u64 v[154:155], v[154:155], 0, s[94:95]
	global_load_ushort v68, v[154:155], off
	s_and_b64 vcc, exec, s[34:35]
	v_mov_b32_e32 v106, v20
	s_cbranch_vccnz .LBB0_400
	v_lshl_add_u64 v[156:157], v[154:155], 0, s[96:97]
	global_load_ushort v106, v[156:157], off
.LBB0_400:
	v_lshl_add_u64 v[154:155], v[154:155], 0, s[94:95]
	global_load_ushort v69, v[154:155], off
	s_and_b64 vcc, exec, s[34:35]
	v_mov_b32_e32 v107, v47
	s_cbranch_vccnz .LBB0_402
	v_lshl_add_u64 v[156:157], v[154:155], 0, s[96:97]
	global_load_ushort v107, v[156:157], off
.LBB0_402:
	v_lshl_add_u64 v[154:155], v[154:155], 0, s[94:95]
	global_load_ushort v70, v[154:155], off
	s_and_b64 vcc, exec, s[34:35]
	v_mov_b32_e32 v108, v21
	s_cbranch_vccnz .LBB0_404
	v_lshl_add_u64 v[156:157], v[154:155], 0, s[96:97]
	global_load_ushort v108, v[156:157], off
.LBB0_404:
	v_lshl_add_u64 v[154:155], v[154:155], 0, s[94:95]
	global_load_ushort v71, v[154:155], off
	s_and_b64 vcc, exec, s[34:35]
	v_mov_b32_e32 v109, v45
	s_cbranch_vccnz .LBB0_406
	v_lshl_add_u64 v[156:157], v[154:155], 0, s[96:97]
	global_load_ushort v109, v[156:157], off
.LBB0_406:
	v_lshl_add_u64 v[154:155], v[154:155], 0, s[94:95]
	global_load_ushort v78, v[154:155], off
	s_and_b64 vcc, exec, s[34:35]
	v_mov_b32_e32 v110, v22
	s_cbranch_vccnz .LBB0_408
	v_lshl_add_u64 v[156:157], v[154:155], 0, s[96:97]
	global_load_ushort v110, v[156:157], off
.LBB0_408:
	v_lshl_add_u64 v[154:155], v[154:155], 0, s[94:95]
	global_load_ushort v82, v[154:155], off
	s_and_b64 vcc, exec, s[34:35]
	v_mov_b32_e32 v111, v43
	s_cbranch_vccnz .LBB0_410
	v_lshl_add_u64 v[156:157], v[154:155], 0, s[96:97]
	global_load_ushort v111, v[156:157], off
.LBB0_410:
	v_lshl_add_u64 v[154:155], v[154:155], 0, s[94:95]
	global_load_ushort v86, v[154:155], off
	s_and_b64 vcc, exec, s[34:35]
	v_mov_b32_e32 v112, v23
	s_cbranch_vccnz .LBB0_412
	v_lshl_add_u64 v[156:157], v[154:155], 0, s[96:97]
	global_load_ushort v112, v[156:157], off
.LBB0_412:
	v_lshl_add_u64 v[154:155], v[154:155], 0, s[94:95]
	global_load_ushort v97, v[154:155], off
	s_and_b64 vcc, exec, s[34:35]
	v_mov_b32_e32 v113, v41
	s_cbranch_vccnz .LBB0_414
	v_lshl_add_u64 v[156:157], v[154:155], 0, s[96:97]
	global_load_ushort v113, v[156:157], off
.LBB0_414:
	v_lshl_add_u64 v[154:155], v[154:155], 0, s[94:95]
	global_load_ushort v98, v[154:155], off
	s_and_b64 vcc, exec, s[34:35]
	v_mov_b32_e32 v114, v37
	s_cbranch_vccnz .LBB0_416
	v_lshl_add_u64 v[156:157], v[154:155], 0, s[96:97]
	global_load_ushort v114, v[156:157], off
.LBB0_416:
	v_lshl_add_u64 v[154:155], v[154:155], 0, s[94:95]
	global_load_ushort v99, v[154:155], off
	s_and_b64 vcc, exec, s[34:35]
	v_mov_b32_e32 v115, v39
	s_cbranch_vccnz .LBB0_418
	v_lshl_add_u64 v[156:157], v[154:155], 0, s[96:97]
	global_load_ushort v115, v[156:157], off

; __global__ void __launch_bounds__(NTHREADS, 2) fwd_megakernel(Params p) {
;     extern __shared__ __attribute__((aligned(16))) unsigned char lds[];
;     cg::grid_group grid = cg::this_grid();
	.amdhsa_kernel _Z14fwd_megakernel6Params
		.amdhsa_group_segment_fixed_size 0
		.amdhsa_private_segment_fixed_size 0
		.amdhsa_kernarg_size 408
		.amdhsa_user_sgpr_count 2
		.amdhsa_user_sgpr_dispatch_ptr 0
		.amdhsa_user_sgpr_queue_ptr 0
		.amdhsa_user_sgpr_kernarg_segment_ptr 1
		.amdhsa_user_sgpr_dispatch_id 0
		.amdhsa_user_sgpr_kernarg_preload_length 0
		.amdhsa_user_sgpr_kernarg_preload_offset 0
		.amdhsa_user_sgpr_private_segment_size 0
		.amdhsa_uses_dynamic_stack 0
		.amdhsa_enable_private_segment 0
		.amdhsa_system_sgpr_workgroup_id_x 1
		.amdhsa_system_sgpr_workgroup_id_y 0
		.amdhsa_system_sgpr_workgroup_id_z 0
		.amdhsa_system_sgpr_workgroup_info 0
		.amdhsa_system_vgpr_workitem_id 2
		.amdhsa_next_free_vgpr 256
		.amdhsa_next_free_sgpr 98
		.amdhsa_accum_offset 256
		.amdhsa_reserve_vcc 1
		.amdhsa_float_round_mode_32 0
		.amdhsa_float_round_mode_16_64 0
		.amdhsa_float_denorm_mode_32 3
		.amdhsa_float_denorm_mode_16_64 3
		.amdhsa_dx10_clamp 1
		.amdhsa_ieee_mode 1
		.amdhsa_fp16_overflow 0
		.amdhsa_tg_split 0
		.amdhsa_exception_fp_ieee_invalid_op 0
		.amdhsa_exception_fp_denorm_src 0
		.amdhsa_exception_fp_ieee_div_zero 0
		.amdhsa_exception_fp_ieee_overflow 0
		.amdhsa_exception_fp_ieee_underflow 0
		.amdhsa_exception_fp_ieee_inexact 0
		.amdhsa_exception_int_div_zero 0
	.end_amdhsa_kernel

; __global__ void __launch_bounds__(NTHREADS, 2) fwd_megakernel(Params p) {
;     extern __shared__ __attribute__((aligned(16))) unsigned char lds[];
;     cg::grid_group grid = cg::this_grid();
amdhsa.kernels:
  - .agpr_count:     0
    .args:
      - .offset:         0
        .size:           152
        .value_kind:     by_value
      - .offset:         152
        .size:           4
        .value_kind:     hidden_block_count_x
      - .offset:         156
        .size:           4
        .value_kind:     hidden_block_count_y
      - .offset:         160
        .size:           4
        .value_kind:     hidden_block_count_z
      - .offset:         164
        .size:           2
        .value_kind:     hidden_group_size_x
      - .offset:         166
        .size:           2
        .value_kind:     hidden_group_size_y
      - .offset:         168
        .size:           2
        .value_kind:     hidden_group_size_z
      - .offset:         170
        .size:           2
        .value_kind:     hidden_remainder_x
      - .offset:         172
        .size:           2
        .value_kind:     hidden_remainder_y
      - .offset:         174
        .size:           2
        .value_kind:     hidden_remainder_z
      - .offset:         192
        .size:           8
        .value_kind:     hidden_global_offset_x
      - .offset:         200
        .size:           8
        .value_kind:     hidden_global_offset_y
      - .offset:         208
        .size:           8
        .value_kind:     hidden_global_offset_z
      - .offset:         216
        .size:           2
        .value_kind:     hidden_grid_dims
      - .offset:         240
        .size:           8
        .value_kind:     hidden_multigrid_sync_arg
      - .offset:         272
        .size:           4
        .value_kind:     hidden_dynamic_lds_size
    .group_segment_fixed_size: 0
    .kernarg_segment_align: 8
    .kernarg_segment_size: 408
    .language:       OpenCL C
    .language_version:
      - 2
      - 0
    .max_flat_workgroup_size: 512
    .name:           _Z14fwd_megakernel6Params
    .private_segment_fixed_size: 0
    .sgpr_count:     104
    .sgpr_spill_count: 0
    .symbol:         _Z14fwd_megakernel6Params.kd
    .uniform_work_group_size: 1
    .uses_dynamic_stack: false
    .vgpr_count:     256
    .vgpr_spill_count: 0
    .wavefront_size: 64
